# q up-projection epilogue loads pipelined one row ahead (vmcnt(2)); MLA parked-Q prologue loads batched
# speedup vs baseline: 1.0185x; 1.0052x over previous
.LBB0_402:
	v_lshl_add_u32 v150, s59, 8, v166
	v_mad_i64_i32 v[182:183], s[4:5], v150, 48, s[20:21]
	v_mov_b32_e32 v240, v182
	v_mov_b32_e32 v241, v183
	s_mov_b64 s[36:37], 0x1800
	v_lshl_add_u64 v[242:243], v[182:183], 0, s[36:37]
	global_load_dwordx4 v[174:177], v[182:183], off offset:32
	global_load_dwordx4 v[178:181], v[182:183], off offset:16
	s_nop 0
	global_load_dwordx4 v[182:185], v[182:183], off
	s_cmp_gt_i32 s42, 3
	s_cselect_b64 s[8:9], -1, 0
	s_lshl_b32 s2, s42, 2
	s_add_i32 s2, s50, s2
	s_mulk_i32 s2, 0xc0
	v_ashrrev_i32_e32 v151, 31, v150
	s_waitcnt vmcnt(0)
	global_load_dwordx4 v[228:231], v[240:241], off offset:768
	global_load_dwordx4 v[232:235], v[240:241], off offset:784
	global_load_dwordx4 v[236:239], v[240:241], off offset:800
	v_add_f32_e32 v152, v182, v183
	v_add_f32_e32 v173, v184, v185
	v_add_f32_e32 v152, v152, v173
	v_add_f32_e32 v173, v178, v179
	v_add_f32_e32 v178, v180, v181
	v_add_f32_e32 v173, v173, v178
	v_add_f32_e32 v152, v152, v173
	v_add_f32_e32 v173, v174, v175
	v_add_f32_e32 v174, v176, v177
	v_add_f32_e32 v173, v173, v174
	v_add_f32_e32 v152, v152, v173
	v_fmamk_f32 v152, v152, 0x3aaaaaab, v171
	v_cmp_gt_f32_e32 vcc, s53, v152
	v_mul_f32_e32 v173, 0x4f800000, v152
	s_nop 0
	v_cndmask_b32_e32 v152, v152, v173, vcc
	v_sqrt_f32_e32 v173, v152
	s_nop 0
	v_add_u32_e32 v174, -1, v173
	v_fma_f32 v175, -v174, v173, v152
	v_cmp_ge_f32_e64 s[4:5], 0, v175
	v_add_u32_e32 v175, 1, v173
	s_nop 0
	v_cndmask_b32_e64 v174, v173, v174, s[4:5]
	v_fma_f32 v173, -v175, v173, v152
	v_cmp_lt_f32_e64 s[4:5], 0, v173
	s_nop 1
	v_cndmask_b32_e64 v173, v174, v175, s[4:5]
	v_mul_f32_e32 v174, 0x37800000, v173
	v_cndmask_b32_e32 v173, v173, v174, vcc
	v_cmp_class_f32_e32 vcc, v152, v172
	s_nop 1
	v_cndmask_b32_e32 v152, v173, v152, vcc
	v_div_scale_f32 v173, s[4:5], v152, v152, s54
	v_rcp_f32_e32 v174, v173
	s_mov_b64 s[4:5], -1
	v_fma_f32 v175, -v173, v174, 1.0
	v_fmac_f32_e32 v174, v175, v174
	v_div_scale_f32 v175, vcc, s54, v152, s54
	v_mul_f32_e32 v176, v175, v174
	v_fma_f32 v177, -v173, v176, v175
	v_fmac_f32_e32 v176, v177, v174
	v_fma_f32 v173, -v173, v176, v175
	v_div_fmas_f32 v173, v173, v174, v176
	v_div_fixup_f32 v152, v173, v152, s54
	s_and_b64 vcc, exec, s[8:9]
	s_cbranch_vccz .LBB0_404
	v_lshlrev_b64 v[182:183], 7, v[150:151]
	v_lshl_add_u64 v[178:179], v[140:141], 0, v[182:183]
	global_load_dwordx4 v[174:177], v[178:179], off
	s_nop 0
	global_load_dwordx4 v[178:181], v[178:179], off offset:16
	v_lshl_add_u64 v[186:187], v[138:139], 0, v[182:183]
	global_load_dwordx4 v[182:185], v[186:187], off
	s_nop 0
	global_load_dwordx4 v[186:189], v[186:187], off offset:16
	v_pk_mul_f32 v[190:191], v[126:127], v[152:153] op_sel_hi:[1,0]
	v_pk_mul_f32 v[194:195], v[118:119], v[152:153] op_sel_hi:[1,0]
	v_pk_mul_f32 v[204:205], v[112:113], v[152:153] op_sel_hi:[1,0]
	v_mov_b64_e32 v[206:207], s[86:87]
	v_pk_mul_f32 v[192:193], v[124:125], v[152:153] op_sel_hi:[1,0]
	v_pk_mul_f32 v[196:197], v[116:117], v[152:153] op_sel_hi:[1,0]
	v_pk_mul_f32 v[200:201], v[120:121], v[152:153] op_sel_hi:[1,0]
	v_pk_mul_f32 v[202:203], v[114:115], v[152:153] op_sel_hi:[1,0]
	v_mad_i64_i32 v[206:207], s[4:5], v150, s55, v[206:207]
	v_pk_mul_f32 v[198:199], v[122:123], v[152:153] op_sel_hi:[1,0]
	v_lshl_add_u64 v[206:207], s[2:3], 1, v[206:207]
	v_lshl_add_u64 v[206:207], v[206:207], 0, v[128:129]
	s_mov_b64 s[4:5], 0
	s_waitcnt vmcnt(3)
	v_pk_mul_f32 v[208:209], v[194:195], v[176:177]
	v_pk_mul_f32 v[176:177], v[190:191], v[176:177]
	s_waitcnt vmcnt(2)
	v_pk_mul_f32 v[214:215], v[204:205], v[178:179]
	v_pk_mul_f32 v[210:211], v[196:197], v[174:175]
	v_pk_mul_f32 v[174:175], v[192:193], v[174:175]
	v_pk_mul_f32 v[212:213], v[202:203], v[180:181]
	s_waitcnt vmcnt(1)
	v_pk_fma_f32 v[190:191], v[190:191], v[184:185], v[208:209] neg_lo:[0,0,1] neg_hi:[0,0,1]
	v_pk_fma_f32 v[184:185], v[194:195], v[184:185], v[176:177]
	s_waitcnt vmcnt(0)
	v_pk_fma_f32 v[176:177], v[200:201], v[186:187], v[214:215] neg_lo:[0,0,1] neg_hi:[0,0,1]
	v_pk_mul_f32 v[180:181], v[198:199], v[180:181]
	v_pk_mul_f32 v[178:179], v[200:201], v[178:179]
	v_pk_fma_f32 v[192:193], v[192:193], v[182:183], v[210:211] neg_lo:[0,0,1] neg_hi:[0,0,1]
	v_pk_fma_f32 v[182:183], v[196:197], v[182:183], v[174:175]
	v_pk_fma_f32 v[194:195], v[198:199], v[188:189], v[212:213] neg_lo:[0,0,1] neg_hi:[0,0,1]
	v_cvt_pk_bf16_f32 v174, v192, v193
	v_cvt_pk_bf16_f32 v175, v190, v191
	v_cvt_pk_bf16_f32 v176, v176, v177
	v_pk_fma_f32 v[180:181], v[202:203], v[188:189], v[180:181]
	v_cvt_pk_bf16_f32 v177, v194, v195
	v_pk_fma_f32 v[178:179], v[204:205], v[186:187], v[178:179]
	global_store_dwordx4 v[206:207], v[174:177], off offset:256
	s_nop 1
	v_cvt_pk_bf16_f32 v174, v182, v183
	v_cvt_pk_bf16_f32 v175, v184, v185
	v_cvt_pk_bf16_f32 v176, v178, v179
	v_cvt_pk_bf16_f32 v177, v180, v181
	global_store_dwordx4 v[206:207], v[174:177], off offset:320

.LBB0_406:
	s_nop 1
	v_or_b32_e32 v112, 16, v150
	v_mad_i64_i32 v[122:123], s[4:5], v112, 48, s[20:21]
	s_waitcnt vmcnt(2)
	v_mov_b32_e32 v114, v228
	v_mov_b32_e32 v115, v229
	v_mov_b32_e32 v116, v230
	v_mov_b32_e32 v117, v231
	v_mov_b32_e32 v118, v232
	v_mov_b32_e32 v119, v233
	v_mov_b32_e32 v120, v234
	v_mov_b32_e32 v121, v235
	v_mov_b32_e32 v122, v236
	v_mov_b32_e32 v123, v237
	v_mov_b32_e32 v124, v238
	v_mov_b32_e32 v125, v239
	global_load_dwordx4 v[216:219], v[240:241], off offset:1536
	global_load_dwordx4 v[220:223], v[240:241], off offset:1552
	global_load_dwordx4 v[224:227], v[240:241], off offset:1568
	v_add_f32_e32 v113, v114, v115
	v_add_f32_e32 v114, v116, v117
	s_nop 0
	v_add_f32_e32 v115, v118, v119
	v_add_f32_e32 v116, v120, v121
	s_nop 0
	v_add_f32_e32 v117, v122, v123
	v_add_f32_e32 v118, v124, v125
	v_add_f32_e32 v113, v113, v114
	v_add_f32_e32 v114, v115, v116
	v_add_f32_e32 v115, v117, v118
	v_add_f32_e32 v113, v113, v114
	v_add_f32_e32 v113, v113, v115
	v_fmamk_f32 v113, v113, 0x3aaaaaab, v171
	v_mul_f32_e32 v114, 0x4f800000, v113
	v_cmp_gt_f32_e32 vcc, s53, v113
	v_cndmask_b32_e64 v116, 0, 1, s[8:9]
	s_nop 0
	v_cndmask_b32_e32 v114, v113, v114, vcc
	v_sqrt_f32_e32 v115, v114
	v_ashrrev_i32_e32 v113, 31, v112
	v_add_u32_e32 v117, -1, v115
	v_add_u32_e32 v118, 1, v115
	v_fma_f32 v119, -v117, v115, v114
	v_fma_f32 v120, -v118, v115, v114
	v_cmp_ge_f32_e64 s[4:5], 0, v119
	s_nop 1
	v_cndmask_b32_e64 v115, v115, v117, s[4:5]
	v_cmp_lt_f32_e64 s[4:5], 0, v120
	s_nop 1
	v_cndmask_b32_e64 v115, v115, v118, s[4:5]
	v_mul_f32_e32 v117, 0x37800000, v115
	v_cndmask_b32_e32 v115, v115, v117, vcc
	v_cmp_class_f32_e32 vcc, v114, v172
	s_nop 1
	v_cndmask_b32_e32 v114, v115, v114, vcc
	v_div_scale_f32 v115, s[4:5], v114, v114, s54
	v_rcp_f32_e32 v117, v115
	v_cmp_ne_u32_e64 s[4:5], 1, v116
	v_div_scale_f32 v116, vcc, s54, v114, s54
	v_fma_f32 v118, -v115, v117, 1.0
	v_fmac_f32_e32 v117, v118, v117
	v_mul_f32_e32 v118, v116, v117
	v_fma_f32 v119, -v115, v118, v116
	v_fmac_f32_e32 v118, v119, v117
	v_fma_f32 v115, -v115, v118, v116
	v_div_fmas_f32 v115, v115, v117, v118
	s_andn2_b64 vcc, exec, s[8:9]
	v_div_fixup_f32 v114, v115, v114, s54
	s_mov_b64 s[8:9], -1
	s_cbranch_vccnz .LBB0_408
	v_lshlrev_b64 v[124:125], 7, v[112:113]
	v_lshl_add_u64 v[120:121], v[140:141], 0, v[124:125]
	global_load_dwordx4 v[116:119], v[120:121], off
	s_nop 0
	global_load_dwordx4 v[120:123], v[120:121], off offset:16
	v_lshl_add_u64 v[174:175], v[138:139], 0, v[124:125]
	global_load_dwordx4 v[124:127], v[174:175], off
	s_nop 0
	global_load_dwordx4 v[174:177], v[174:175], off offset:16
	v_pk_mul_f32 v[178:179], v[110:111], v[114:115] op_sel_hi:[1,0]
	v_pk_mul_f32 v[182:183], v[102:103], v[114:115] op_sel_hi:[1,0]
	v_pk_mul_f32 v[192:193], v[96:97], v[114:115] op_sel_hi:[1,0]
	v_mov_b64_e32 v[194:195], s[86:87]
	v_pk_mul_f32 v[180:181], v[108:109], v[114:115] op_sel_hi:[1,0]
	v_pk_mul_f32 v[184:185], v[100:101], v[114:115] op_sel_hi:[1,0]
	v_pk_mul_f32 v[188:189], v[104:105], v[114:115] op_sel_hi:[1,0]
	v_pk_mul_f32 v[190:191], v[98:99], v[114:115] op_sel_hi:[1,0]
	v_mad_i64_i32 v[194:195], s[8:9], v112, s55, v[194:195]
	v_pk_mul_f32 v[186:187], v[106:107], v[114:115] op_sel_hi:[1,0]
	v_lshl_add_u64 v[194:195], s[2:3], 1, v[194:195]
	v_lshl_add_u64 v[194:195], v[194:195], 0, v[128:129]
	s_mov_b64 s[8:9], 0
	s_waitcnt vmcnt(3)
	v_pk_mul_f32 v[196:197], v[182:183], v[118:119]
	v_pk_mul_f32 v[118:119], v[178:179], v[118:119]
	s_waitcnt vmcnt(2)
	v_pk_mul_f32 v[202:203], v[192:193], v[120:121]
	v_pk_mul_f32 v[198:199], v[184:185], v[116:117]
	v_pk_mul_f32 v[116:117], v[180:181], v[116:117]
	v_pk_mul_f32 v[200:201], v[190:191], v[122:123]
	s_waitcnt vmcnt(1)
	v_pk_fma_f32 v[178:179], v[178:179], v[126:127], v[196:197] neg_lo:[0,0,1] neg_hi:[0,0,1]
	v_pk_fma_f32 v[126:127], v[182:183], v[126:127], v[118:119]
	s_waitcnt vmcnt(0)
	v_pk_fma_f32 v[118:119], v[188:189], v[174:175], v[202:203] neg_lo:[0,0,1] neg_hi:[0,0,1]
	v_pk_mul_f32 v[122:123], v[186:187], v[122:123]
	v_pk_mul_f32 v[120:121], v[188:189], v[120:121]
	v_pk_fma_f32 v[180:181], v[180:181], v[124:125], v[198:199] neg_lo:[0,0,1] neg_hi:[0,0,1]
	v_pk_fma_f32 v[124:125], v[184:185], v[124:125], v[116:117]
	v_pk_fma_f32 v[182:183], v[186:187], v[176:177], v[200:201] neg_lo:[0,0,1] neg_hi:[0,0,1]
	v_cvt_pk_bf16_f32 v116, v180, v181
	v_cvt_pk_bf16_f32 v117, v178, v179
	v_cvt_pk_bf16_f32 v118, v118, v119
	v_pk_fma_f32 v[122:123], v[190:191], v[176:177], v[122:123]
	v_cvt_pk_bf16_f32 v119, v182, v183
	v_pk_fma_f32 v[120:121], v[192:193], v[174:175], v[120:121]
	global_store_dwordx4 v[194:195], v[116:119], off offset:256
	s_nop 1
	v_cvt_pk_bf16_f32 v116, v124, v125
	v_cvt_pk_bf16_f32 v117, v126, v127
	v_cvt_pk_bf16_f32 v118, v120, v121
	v_cvt_pk_bf16_f32 v119, v122, v123
	global_store_dwordx4 v[194:195], v[116:119], off offset:320

.LBB0_410:
	s_nop 1
	v_or_b32_e32 v96, 32, v150
	v_mad_i64_i32 v[106:107], s[8:9], v96, 48, s[20:21]
	s_waitcnt vmcnt(2)
	v_mov_b32_e32 v98, v216
	v_mov_b32_e32 v99, v217
	v_mov_b32_e32 v100, v218
	v_mov_b32_e32 v101, v219
	v_mov_b32_e32 v102, v220
	v_mov_b32_e32 v103, v221
	v_mov_b32_e32 v104, v222
	v_mov_b32_e32 v105, v223
	v_mov_b32_e32 v106, v224
	v_mov_b32_e32 v107, v225
	v_mov_b32_e32 v108, v226
	v_mov_b32_e32 v109, v227
	global_load_dwordx4 v[228:231], v[240:241], off offset:2304
	global_load_dwordx4 v[232:235], v[240:241], off offset:2320
	global_load_dwordx4 v[236:239], v[240:241], off offset:2336
	v_add_f32_e32 v97, v98, v99
	v_add_f32_e32 v98, v100, v101
	s_nop 0
	v_add_f32_e32 v99, v102, v103
	v_add_f32_e32 v100, v104, v105
	s_nop 0
	v_add_f32_e32 v101, v106, v107
	v_add_f32_e32 v102, v108, v109
	v_add_f32_e32 v97, v97, v98
	v_add_f32_e32 v98, v99, v100
	v_add_f32_e32 v99, v101, v102
	v_add_f32_e32 v97, v97, v98
	v_add_f32_e32 v97, v97, v99
	v_fmamk_f32 v97, v97, 0x3aaaaaab, v171
	v_mul_f32_e32 v98, 0x4f800000, v97
	v_cmp_gt_f32_e32 vcc, s53, v97
	s_nop 1
	v_cndmask_b32_e32 v97, v97, v98, vcc
	v_sqrt_f32_e32 v98, v97
	s_nop 0
	v_add_u32_e32 v99, -1, v98
	v_add_u32_e32 v100, 1, v98
	v_fma_f32 v101, -v99, v98, v97
	v_fma_f32 v102, -v100, v98, v97
	v_cmp_ge_f32_e64 s[8:9], 0, v101
	s_nop 1
	v_cndmask_b32_e64 v98, v98, v99, s[8:9]
	v_cmp_lt_f32_e64 s[8:9], 0, v102
	s_nop 1
	v_cndmask_b32_e64 v98, v98, v100, s[8:9]
	v_mul_f32_e32 v99, 0x37800000, v98
	v_cndmask_b32_e32 v98, v98, v99, vcc
	v_cmp_class_f32_e32 vcc, v97, v172
	s_nop 1
	v_cndmask_b32_e32 v98, v98, v97, vcc
	v_div_scale_f32 v99, s[8:9], v98, v98, s54
	v_rcp_f32_e32 v100, v99
	v_div_scale_f32 v101, vcc, s54, v98, s54
	v_ashrrev_i32_e32 v97, 31, v96
	v_fma_f32 v102, -v99, v100, 1.0
	v_fmac_f32_e32 v100, v102, v100
	v_mul_f32_e32 v102, v101, v100
	v_fma_f32 v103, -v99, v102, v101
	v_fmac_f32_e32 v102, v103, v100
	v_fma_f32 v99, -v99, v102, v101
	v_div_fmas_f32 v99, v99, v100, v102
	s_and_b64 vcc, exec, s[4:5]
	v_div_fixup_f32 v98, v99, v98, s54
	s_mov_b64 s[8:9], -1
	s_cbranch_vccnz .LBB0_412
	v_lshlrev_b64 v[108:109], 7, v[96:97]
	v_lshl_add_u64 v[104:105], v[140:141], 0, v[108:109]
	global_load_dwordx4 v[100:103], v[104:105], off
	s_nop 0
	global_load_dwordx4 v[104:107], v[104:105], off offset:16
	v_lshl_add_u64 v[112:113], v[138:139], 0, v[108:109]
	global_load_dwordx4 v[108:111], v[112:113], off
	s_nop 0
	global_load_dwordx4 v[112:115], v[112:113], off offset:16
	v_pk_mul_f32 v[116:117], v[94:95], v[98:99] op_sel_hi:[1,0]
	v_pk_mul_f32 v[120:121], v[86:87], v[98:99] op_sel_hi:[1,0]
	v_pk_mul_f32 v[176:177], v[80:81], v[98:99] op_sel_hi:[1,0]
	v_mov_b64_e32 v[178:179], s[86:87]
	v_pk_mul_f32 v[118:119], v[92:93], v[98:99] op_sel_hi:[1,0]
	v_pk_mul_f32 v[122:123], v[84:85], v[98:99] op_sel_hi:[1,0]
	v_pk_mul_f32 v[126:127], v[88:89], v[98:99] op_sel_hi:[1,0]
	v_pk_mul_f32 v[174:175], v[82:83], v[98:99] op_sel_hi:[1,0]
	v_mad_i64_i32 v[178:179], s[8:9], v96, s55, v[178:179]
	v_pk_mul_f32 v[124:125], v[90:91], v[98:99] op_sel_hi:[1,0]
	v_lshl_add_u64 v[178:179], s[2:3], 1, v[178:179]
	v_lshl_add_u64 v[178:179], v[178:179], 0, v[128:129]
	s_mov_b64 s[8:9], 0
	s_waitcnt vmcnt(3)
	v_pk_mul_f32 v[180:181], v[120:121], v[102:103]
	v_pk_mul_f32 v[102:103], v[116:117], v[102:103]
	s_waitcnt vmcnt(2)
	v_pk_mul_f32 v[186:187], v[176:177], v[104:105]
	v_pk_mul_f32 v[182:183], v[122:123], v[100:101]
	v_pk_mul_f32 v[100:101], v[118:119], v[100:101]
	v_pk_mul_f32 v[184:185], v[174:175], v[106:107]
	s_waitcnt vmcnt(1)
	v_pk_fma_f32 v[116:117], v[116:117], v[110:111], v[180:181] neg_lo:[0,0,1] neg_hi:[0,0,1]
	v_pk_fma_f32 v[110:111], v[120:121], v[110:111], v[102:103]
	s_waitcnt vmcnt(0)
	v_pk_fma_f32 v[102:103], v[126:127], v[112:113], v[186:187] neg_lo:[0,0,1] neg_hi:[0,0,1]
	v_pk_mul_f32 v[106:107], v[124:125], v[106:107]
	v_pk_mul_f32 v[104:105], v[126:127], v[104:105]
	v_pk_fma_f32 v[118:119], v[118:119], v[108:109], v[182:183] neg_lo:[0,0,1] neg_hi:[0,0,1]
	v_pk_fma_f32 v[108:109], v[122:123], v[108:109], v[100:101]
	v_pk_fma_f32 v[120:121], v[124:125], v[114:115], v[184:185] neg_lo:[0,0,1] neg_hi:[0,0,1]
	v_cvt_pk_bf16_f32 v100, v118, v119
	v_cvt_pk_bf16_f32 v101, v116, v117
	v_cvt_pk_bf16_f32 v102, v102, v103
	v_pk_fma_f32 v[106:107], v[174:175], v[114:115], v[106:107]
	v_cvt_pk_bf16_f32 v103, v120, v121
	v_pk_fma_f32 v[104:105], v[176:177], v[112:113], v[104:105]
	global_store_dwordx4 v[178:179], v[100:103], off offset:256
	s_nop 1
	v_cvt_pk_bf16_f32 v100, v108, v109
	v_cvt_pk_bf16_f32 v101, v110, v111
	v_cvt_pk_bf16_f32 v102, v104, v105
	v_cvt_pk_bf16_f32 v103, v106, v107
	global_store_dwordx4 v[178:179], v[100:103], off offset:320

.LBB0_414:
	s_nop 1
	v_or_b32_e32 v80, 48, v150
	v_mad_i64_i32 v[90:91], s[8:9], v80, 48, s[20:21]
	s_waitcnt vmcnt(2)
	v_mov_b32_e32 v82, v228
	v_mov_b32_e32 v83, v229
	v_mov_b32_e32 v84, v230
	v_mov_b32_e32 v85, v231
	v_mov_b32_e32 v86, v232
	v_mov_b32_e32 v87, v233
	v_mov_b32_e32 v88, v234
	v_mov_b32_e32 v89, v235
	v_mov_b32_e32 v90, v236
	v_mov_b32_e32 v91, v237
	v_mov_b32_e32 v92, v238
	v_mov_b32_e32 v93, v239
	global_load_dwordx4 v[216:219], v[242:243], off offset:0
	global_load_dwordx4 v[220:223], v[242:243], off offset:16
	global_load_dwordx4 v[224:227], v[242:243], off offset:32
	v_add_f32_e32 v81, v82, v83
	v_add_f32_e32 v82, v84, v85
	s_nop 0
	v_add_f32_e32 v83, v86, v87
	v_add_f32_e32 v84, v88, v89
	s_nop 0
	v_add_f32_e32 v85, v90, v91
	v_add_f32_e32 v86, v92, v93
	v_add_f32_e32 v81, v81, v82
	v_add_f32_e32 v82, v83, v84
	v_add_f32_e32 v83, v85, v86
	v_add_f32_e32 v81, v81, v82
	v_add_f32_e32 v81, v81, v83
	v_fmamk_f32 v81, v81, 0x3aaaaaab, v171
	v_mul_f32_e32 v82, 0x4f800000, v81
	v_cmp_gt_f32_e32 vcc, s53, v81
	s_nop 1
	v_cndmask_b32_e32 v81, v81, v82, vcc
	v_sqrt_f32_e32 v82, v81
	s_nop 0
	v_add_u32_e32 v83, -1, v82
	v_add_u32_e32 v84, 1, v82
	v_fma_f32 v85, -v83, v82, v81
	v_fma_f32 v86, -v84, v82, v81
	v_cmp_ge_f32_e64 s[8:9], 0, v85
	s_nop 1
	v_cndmask_b32_e64 v82, v82, v83, s[8:9]
	v_cmp_lt_f32_e64 s[8:9], 0, v86
	s_nop 1
	v_cndmask_b32_e64 v82, v82, v84, s[8:9]
	v_mul_f32_e32 v83, 0x37800000, v82
	v_cndmask_b32_e32 v82, v82, v83, vcc
	v_cmp_class_f32_e32 vcc, v81, v172
	s_nop 1
	v_cndmask_b32_e32 v82, v82, v81, vcc
	v_div_scale_f32 v83, s[8:9], v82, v82, s54
	v_rcp_f32_e32 v84, v83
	v_div_scale_f32 v85, vcc, s54, v82, s54
	v_ashrrev_i32_e32 v81, 31, v80
	v_fma_f32 v86, -v83, v84, 1.0
	v_fmac_f32_e32 v84, v86, v84
	v_mul_f32_e32 v86, v85, v84
	v_fma_f32 v87, -v83, v86, v85
	v_fmac_f32_e32 v86, v87, v84
	v_fma_f32 v83, -v83, v86, v85
	v_div_fmas_f32 v83, v83, v84, v86
	s_and_b64 vcc, exec, s[4:5]
	v_div_fixup_f32 v82, v83, v82, s54
	s_mov_b64 s[8:9], -1
	s_cbranch_vccnz .LBB0_416
	v_lshlrev_b64 v[92:93], 7, v[80:81]
	v_lshl_add_u64 v[88:89], v[140:141], 0, v[92:93]
	global_load_dwordx4 v[84:87], v[88:89], off
	s_nop 0
	global_load_dwordx4 v[88:91], v[88:89], off offset:16
	v_lshl_add_u64 v[96:97], v[138:139], 0, v[92:93]
	global_load_dwordx4 v[92:95], v[96:97], off
	s_nop 0
	global_load_dwordx4 v[96:99], v[96:97], off offset:16
	v_pk_mul_f32 v[100:101], v[78:79], v[82:83] op_sel_hi:[1,0]
	v_pk_mul_f32 v[104:105], v[70:71], v[82:83] op_sel_hi:[1,0]
	v_pk_mul_f32 v[114:115], v[64:65], v[82:83] op_sel_hi:[1,0]
	v_mov_b64_e32 v[116:117], s[86:87]
	v_pk_mul_f32 v[102:103], v[76:77], v[82:83] op_sel_hi:[1,0]
	v_pk_mul_f32 v[106:107], v[68:69], v[82:83] op_sel_hi:[1,0]
	v_pk_mul_f32 v[110:111], v[72:73], v[82:83] op_sel_hi:[1,0]
	v_pk_mul_f32 v[112:113], v[66:67], v[82:83] op_sel_hi:[1,0]
	v_mad_i64_i32 v[116:117], s[8:9], v80, s55, v[116:117]
	v_pk_mul_f32 v[108:109], v[74:75], v[82:83] op_sel_hi:[1,0]
	v_lshl_add_u64 v[116:117], s[2:3], 1, v[116:117]
	v_lshl_add_u64 v[116:117], v[116:117], 0, v[128:129]
	s_mov_b64 s[8:9], 0
	s_waitcnt vmcnt(3)
	v_pk_mul_f32 v[118:119], v[104:105], v[86:87]
	v_pk_mul_f32 v[86:87], v[100:101], v[86:87]
	s_waitcnt vmcnt(2)
	v_pk_mul_f32 v[124:125], v[114:115], v[88:89]
	v_pk_mul_f32 v[120:121], v[106:107], v[84:85]
	v_pk_mul_f32 v[84:85], v[102:103], v[84:85]
	v_pk_mul_f32 v[122:123], v[112:113], v[90:91]
	s_waitcnt vmcnt(1)
	v_pk_fma_f32 v[100:101], v[100:101], v[94:95], v[118:119] neg_lo:[0,0,1] neg_hi:[0,0,1]
	v_pk_fma_f32 v[94:95], v[104:105], v[94:95], v[86:87]
	s_waitcnt vmcnt(0)
	v_pk_fma_f32 v[86:87], v[110:111], v[96:97], v[124:125] neg_lo:[0,0,1] neg_hi:[0,0,1]
	v_pk_mul_f32 v[90:91], v[108:109], v[90:91]
	v_pk_mul_f32 v[88:89], v[110:111], v[88:89]
	v_pk_fma_f32 v[102:103], v[102:103], v[92:93], v[120:121] neg_lo:[0,0,1] neg_hi:[0,0,1]
	v_pk_fma_f32 v[92:93], v[106:107], v[92:93], v[84:85]
	v_pk_fma_f32 v[104:105], v[108:109], v[98:99], v[122:123] neg_lo:[0,0,1] neg_hi:[0,0,1]
	v_cvt_pk_bf16_f32 v84, v102, v103
	v_cvt_pk_bf16_f32 v85, v100, v101
	v_cvt_pk_bf16_f32 v86, v86, v87
	v_pk_fma_f32 v[90:91], v[112:113], v[98:99], v[90:91]
	v_cvt_pk_bf16_f32 v87, v104, v105
	v_pk_fma_f32 v[88:89], v[114:115], v[96:97], v[88:89]
	global_store_dwordx4 v[116:117], v[84:87], off offset:256
	s_nop 1
	v_cvt_pk_bf16_f32 v84, v92, v93
	v_cvt_pk_bf16_f32 v85, v94, v95
	v_cvt_pk_bf16_f32 v86, v88, v89
	v_cvt_pk_bf16_f32 v87, v90, v91
	global_store_dwordx4 v[116:117], v[84:87], off offset:320

.LBB0_418:
	s_nop 1
	v_add_u32_e32 v64, 0x80, v150
	v_mad_i64_i32 v[74:75], s[8:9], v64, 48, s[20:21]
	s_waitcnt vmcnt(2)
	v_mov_b32_e32 v66, v216
	v_mov_b32_e32 v67, v217
	v_mov_b32_e32 v68, v218
	v_mov_b32_e32 v69, v219
	v_mov_b32_e32 v70, v220
	v_mov_b32_e32 v71, v221
	v_mov_b32_e32 v72, v222
	v_mov_b32_e32 v73, v223
	v_mov_b32_e32 v74, v224
	v_mov_b32_e32 v75, v225
	v_mov_b32_e32 v76, v226
	v_mov_b32_e32 v77, v227
	global_load_dwordx4 v[228:231], v[242:243], off offset:768
	global_load_dwordx4 v[232:235], v[242:243], off offset:784
	global_load_dwordx4 v[236:239], v[242:243], off offset:800
	v_add_f32_e32 v65, v66, v67
	v_add_f32_e32 v66, v68, v69
	s_nop 0
	v_add_f32_e32 v67, v70, v71
	v_add_f32_e32 v68, v72, v73
	s_nop 0
	v_add_f32_e32 v69, v74, v75
	v_add_f32_e32 v70, v76, v77
	v_add_f32_e32 v65, v65, v66
	v_add_f32_e32 v66, v67, v68
	v_add_f32_e32 v67, v69, v70
	v_add_f32_e32 v65, v65, v66
	v_add_f32_e32 v65, v65, v67
	v_fmamk_f32 v65, v65, 0x3aaaaaab, v171
	v_mul_f32_e32 v66, 0x4f800000, v65
	v_cmp_gt_f32_e32 vcc, s53, v65
	s_nop 1
	v_cndmask_b32_e32 v65, v65, v66, vcc
	v_sqrt_f32_e32 v66, v65
	s_nop 0
	v_add_u32_e32 v67, -1, v66
	v_add_u32_e32 v68, 1, v66
	v_fma_f32 v69, -v67, v66, v65
	v_fma_f32 v70, -v68, v66, v65
	v_cmp_ge_f32_e64 s[8:9], 0, v69
	s_nop 1
	v_cndmask_b32_e64 v66, v66, v67, s[8:9]
	v_cmp_lt_f32_e64 s[8:9], 0, v70
	s_nop 1
	v_cndmask_b32_e64 v66, v66, v68, s[8:9]
	v_mul_f32_e32 v67, 0x37800000, v66
	v_cndmask_b32_e32 v66, v66, v67, vcc
	v_cmp_class_f32_e32 vcc, v65, v172
	s_nop 1
	v_cndmask_b32_e32 v66, v66, v65, vcc
	v_div_scale_f32 v67, s[8:9], v66, v66, s54
	v_rcp_f32_e32 v68, v67
	v_div_scale_f32 v69, vcc, s54, v66, s54
	v_ashrrev_i32_e32 v65, 31, v64
	v_fma_f32 v70, -v67, v68, 1.0
	v_fmac_f32_e32 v68, v70, v68
	v_mul_f32_e32 v70, v69, v68
	v_fma_f32 v71, -v67, v70, v69
	v_fmac_f32_e32 v70, v71, v68
	v_fma_f32 v67, -v67, v70, v69
	v_div_fmas_f32 v67, v67, v68, v70
	s_and_b64 vcc, exec, s[4:5]
	v_div_fixup_f32 v66, v67, v66, s54
	s_mov_b64 s[8:9], -1
	s_cbranch_vccnz .LBB0_420
	v_lshlrev_b64 v[76:77], 7, v[64:65]
	v_lshl_add_u64 v[72:73], v[140:141], 0, v[76:77]
	global_load_dwordx4 v[68:71], v[72:73], off
	s_nop 0
	global_load_dwordx4 v[72:75], v[72:73], off offset:16
	v_lshl_add_u64 v[80:81], v[138:139], 0, v[76:77]
	global_load_dwordx4 v[76:79], v[80:81], off
	s_nop 0
	global_load_dwordx4 v[80:83], v[80:81], off offset:16
	v_pk_mul_f32 v[84:85], v[62:63], v[66:67] op_sel_hi:[1,0]
	v_pk_mul_f32 v[88:89], v[54:55], v[66:67] op_sel_hi:[1,0]
	v_pk_mul_f32 v[98:99], v[48:49], v[66:67] op_sel_hi:[1,0]
	v_mov_b64_e32 v[100:101], s[86:87]
	v_pk_mul_f32 v[86:87], v[60:61], v[66:67] op_sel_hi:[1,0]
	v_pk_mul_f32 v[90:91], v[52:53], v[66:67] op_sel_hi:[1,0]
	v_pk_mul_f32 v[94:95], v[56:57], v[66:67] op_sel_hi:[1,0]
	v_pk_mul_f32 v[96:97], v[50:51], v[66:67] op_sel_hi:[1,0]
	v_mad_i64_i32 v[100:101], s[8:9], v64, s55, v[100:101]
	v_pk_mul_f32 v[92:93], v[58:59], v[66:67] op_sel_hi:[1,0]
	v_lshl_add_u64 v[100:101], s[2:3], 1, v[100:101]
	v_lshl_add_u64 v[100:101], v[100:101], 0, v[128:129]
	s_mov_b64 s[8:9], 0
	s_waitcnt vmcnt(3)
	v_pk_mul_f32 v[102:103], v[88:89], v[70:71]
	v_pk_mul_f32 v[70:71], v[84:85], v[70:71]
	s_waitcnt vmcnt(2)
	v_pk_mul_f32 v[108:109], v[98:99], v[72:73]
	v_pk_mul_f32 v[104:105], v[90:91], v[68:69]
	v_pk_mul_f32 v[68:69], v[86:87], v[68:69]
	v_pk_mul_f32 v[106:107], v[96:97], v[74:75]
	s_waitcnt vmcnt(1)
	v_pk_fma_f32 v[84:85], v[84:85], v[78:79], v[102:103] neg_lo:[0,0,1] neg_hi:[0,0,1]
	v_pk_fma_f32 v[78:79], v[88:89], v[78:79], v[70:71]
	s_waitcnt vmcnt(0)
	v_pk_fma_f32 v[70:71], v[94:95], v[80:81], v[108:109] neg_lo:[0,0,1] neg_hi:[0,0,1]
	v_pk_mul_f32 v[74:75], v[92:93], v[74:75]
	v_pk_mul_f32 v[72:73], v[94:95], v[72:73]
	v_pk_fma_f32 v[86:87], v[86:87], v[76:77], v[104:105] neg_lo:[0,0,1] neg_hi:[0,0,1]
	v_pk_fma_f32 v[76:77], v[90:91], v[76:77], v[68:69]
	v_pk_fma_f32 v[88:89], v[92:93], v[82:83], v[106:107] neg_lo:[0,0,1] neg_hi:[0,0,1]
	v_cvt_pk_bf16_f32 v68, v86, v87
	v_cvt_pk_bf16_f32 v69, v84, v85
	v_cvt_pk_bf16_f32 v70, v70, v71
	v_pk_fma_f32 v[74:75], v[96:97], v[82:83], v[74:75]
	v_cvt_pk_bf16_f32 v71, v88, v89
	v_pk_fma_f32 v[72:73], v[98:99], v[80:81], v[72:73]
	global_store_dwordx4 v[100:101], v[68:71], off offset:256
	s_nop 1
	v_cvt_pk_bf16_f32 v68, v76, v77
	v_cvt_pk_bf16_f32 v69, v78, v79
	v_cvt_pk_bf16_f32 v70, v72, v73
	v_cvt_pk_bf16_f32 v71, v74, v75
	global_store_dwordx4 v[100:101], v[68:71], off offset:320

.LBB0_422:
	s_nop 1
	v_add_u32_e32 v48, 0x90, v150
	v_mad_i64_i32 v[58:59], s[8:9], v48, 48, s[20:21]
	s_waitcnt vmcnt(2)
	v_mov_b32_e32 v50, v228
	v_mov_b32_e32 v51, v229
	v_mov_b32_e32 v52, v230
	v_mov_b32_e32 v53, v231
	v_mov_b32_e32 v54, v232
	v_mov_b32_e32 v55, v233
	v_mov_b32_e32 v56, v234
	v_mov_b32_e32 v57, v235
	v_mov_b32_e32 v58, v236
	v_mov_b32_e32 v59, v237
	v_mov_b32_e32 v60, v238
	v_mov_b32_e32 v61, v239
	global_load_dwordx4 v[216:219], v[242:243], off offset:1536
	global_load_dwordx4 v[220:223], v[242:243], off offset:1552
	global_load_dwordx4 v[224:227], v[242:243], off offset:1568
	v_add_f32_e32 v49, v50, v51
	v_add_f32_e32 v50, v52, v53
	s_nop 0
	v_add_f32_e32 v51, v54, v55
	v_add_f32_e32 v52, v56, v57
	s_nop 0
	v_add_f32_e32 v53, v58, v59
	v_add_f32_e32 v54, v60, v61
	v_add_f32_e32 v49, v49, v50
	v_add_f32_e32 v50, v51, v52
	v_add_f32_e32 v51, v53, v54
	v_add_f32_e32 v49, v49, v50
	v_add_f32_e32 v49, v49, v51
	v_fmamk_f32 v49, v49, 0x3aaaaaab, v171
	v_mul_f32_e32 v50, 0x4f800000, v49
	v_cmp_gt_f32_e32 vcc, s53, v49
	s_nop 1
	v_cndmask_b32_e32 v49, v49, v50, vcc
	v_sqrt_f32_e32 v50, v49
	s_nop 0
	v_add_u32_e32 v51, -1, v50
	v_add_u32_e32 v52, 1, v50
	v_fma_f32 v53, -v51, v50, v49
	v_fma_f32 v54, -v52, v50, v49
	v_cmp_ge_f32_e64 s[8:9], 0, v53
	s_nop 1
	v_cndmask_b32_e64 v50, v50, v51, s[8:9]
	v_cmp_lt_f32_e64 s[8:9], 0, v54
	s_nop 1
	v_cndmask_b32_e64 v50, v50, v52, s[8:9]
	v_mul_f32_e32 v51, 0x37800000, v50
	v_cndmask_b32_e32 v50, v50, v51, vcc
	v_cmp_class_f32_e32 vcc, v49, v172
	s_nop 1
	v_cndmask_b32_e32 v50, v50, v49, vcc
	v_div_scale_f32 v51, s[8:9], v50, v50, s54
	v_rcp_f32_e32 v52, v51
	v_div_scale_f32 v53, vcc, s54, v50, s54
	v_ashrrev_i32_e32 v49, 31, v48
	v_fma_f32 v54, -v51, v52, 1.0
	v_fmac_f32_e32 v52, v54, v52
	v_mul_f32_e32 v54, v53, v52
	v_fma_f32 v55, -v51, v54, v53
	v_fmac_f32_e32 v54, v55, v52
	v_fma_f32 v51, -v51, v54, v53
	v_div_fmas_f32 v51, v51, v52, v54
	s_and_b64 vcc, exec, s[4:5]
	v_div_fixup_f32 v50, v51, v50, s54
	s_mov_b64 s[8:9], -1
	s_cbranch_vccnz .LBB0_424
	v_lshlrev_b64 v[60:61], 7, v[48:49]
	v_lshl_add_u64 v[56:57], v[140:141], 0, v[60:61]
	global_load_dwordx4 v[52:55], v[56:57], off
	s_nop 0
	global_load_dwordx4 v[56:59], v[56:57], off offset:16
	v_lshl_add_u64 v[64:65], v[138:139], 0, v[60:61]
	global_load_dwordx4 v[60:63], v[64:65], off
	s_nop 0
	global_load_dwordx4 v[64:67], v[64:65], off offset:16
	v_pk_mul_f32 v[68:69], v[46:47], v[50:51] op_sel_hi:[1,0]
	v_pk_mul_f32 v[72:73], v[38:39], v[50:51] op_sel_hi:[1,0]
	v_pk_mul_f32 v[82:83], v[32:33], v[50:51] op_sel_hi:[1,0]
	v_mov_b64_e32 v[84:85], s[86:87]
	v_pk_mul_f32 v[70:71], v[44:45], v[50:51] op_sel_hi:[1,0]
	v_pk_mul_f32 v[74:75], v[36:37], v[50:51] op_sel_hi:[1,0]
	v_pk_mul_f32 v[78:79], v[40:41], v[50:51] op_sel_hi:[1,0]
	v_pk_mul_f32 v[80:81], v[34:35], v[50:51] op_sel_hi:[1,0]
	v_mad_i64_i32 v[84:85], s[8:9], v48, s55, v[84:85]
	v_pk_mul_f32 v[76:77], v[42:43], v[50:51] op_sel_hi:[1,0]
	v_lshl_add_u64 v[84:85], s[2:3], 1, v[84:85]
	v_lshl_add_u64 v[84:85], v[84:85], 0, v[128:129]
	s_mov_b64 s[8:9], 0
	s_waitcnt vmcnt(3)
	v_pk_mul_f32 v[86:87], v[72:73], v[54:55]
	v_pk_mul_f32 v[54:55], v[68:69], v[54:55]
	s_waitcnt vmcnt(2)
	v_pk_mul_f32 v[92:93], v[82:83], v[56:57]
	v_pk_mul_f32 v[88:89], v[74:75], v[52:53]
	v_pk_mul_f32 v[52:53], v[70:71], v[52:53]
	v_pk_mul_f32 v[90:91], v[80:81], v[58:59]
	s_waitcnt vmcnt(1)
	v_pk_fma_f32 v[68:69], v[68:69], v[62:63], v[86:87] neg_lo:[0,0,1] neg_hi:[0,0,1]
	v_pk_fma_f32 v[62:63], v[72:73], v[62:63], v[54:55]
	s_waitcnt vmcnt(0)
	v_pk_fma_f32 v[54:55], v[78:79], v[64:65], v[92:93] neg_lo:[0,0,1] neg_hi:[0,0,1]
	v_pk_mul_f32 v[58:59], v[76:77], v[58:59]
	v_pk_mul_f32 v[56:57], v[78:79], v[56:57]
	v_pk_fma_f32 v[70:71], v[70:71], v[60:61], v[88:89] neg_lo:[0,0,1] neg_hi:[0,0,1]
	v_pk_fma_f32 v[60:61], v[74:75], v[60:61], v[52:53]
	v_pk_fma_f32 v[72:73], v[76:77], v[66:67], v[90:91] neg_lo:[0,0,1] neg_hi:[0,0,1]
	v_cvt_pk_bf16_f32 v52, v70, v71
	v_cvt_pk_bf16_f32 v53, v68, v69
	v_cvt_pk_bf16_f32 v54, v54, v55
	v_pk_fma_f32 v[58:59], v[80:81], v[66:67], v[58:59]
	v_cvt_pk_bf16_f32 v55, v72, v73
	v_pk_fma_f32 v[56:57], v[82:83], v[64:65], v[56:57]
	global_store_dwordx4 v[84:85], v[52:55], off offset:256
	s_nop 1
	v_cvt_pk_bf16_f32 v52, v60, v61
	v_cvt_pk_bf16_f32 v53, v62, v63
	v_cvt_pk_bf16_f32 v54, v56, v57
	v_cvt_pk_bf16_f32 v55, v58, v59
	global_store_dwordx4 v[84:85], v[52:55], off offset:320

.LBB0_426:
	s_nop 1
	v_add_u32_e32 v32, 0xa0, v150
	v_mad_i64_i32 v[42:43], s[8:9], v32, 48, s[20:21]
	s_waitcnt vmcnt(2)
	v_mov_b32_e32 v34, v216
	v_mov_b32_e32 v35, v217
	v_mov_b32_e32 v36, v218
	v_mov_b32_e32 v37, v219
	v_mov_b32_e32 v38, v220
	v_mov_b32_e32 v39, v221
	v_mov_b32_e32 v40, v222
	v_mov_b32_e32 v41, v223
	v_mov_b32_e32 v42, v224
	v_mov_b32_e32 v43, v225
	v_mov_b32_e32 v44, v226
	v_mov_b32_e32 v45, v227
	global_load_dwordx4 v[228:231], v[242:243], off offset:2304
	global_load_dwordx4 v[232:235], v[242:243], off offset:2320
	global_load_dwordx4 v[236:239], v[242:243], off offset:2336
	v_add_f32_e32 v33, v34, v35
	v_add_f32_e32 v34, v36, v37
	s_nop 0
	v_add_f32_e32 v35, v38, v39
	v_add_f32_e32 v36, v40, v41
	s_nop 0
	v_add_f32_e32 v37, v42, v43
	v_add_f32_e32 v38, v44, v45
	v_add_f32_e32 v33, v33, v34
	v_add_f32_e32 v34, v35, v36
	v_add_f32_e32 v35, v37, v38
	v_add_f32_e32 v33, v33, v34
	v_add_f32_e32 v33, v33, v35
	v_fmamk_f32 v33, v33, 0x3aaaaaab, v171
	v_mul_f32_e32 v34, 0x4f800000, v33
	v_cmp_gt_f32_e32 vcc, s53, v33
	s_nop 1
	v_cndmask_b32_e32 v33, v33, v34, vcc
	v_sqrt_f32_e32 v34, v33
	s_nop 0
	v_add_u32_e32 v35, -1, v34
	v_add_u32_e32 v36, 1, v34
	v_fma_f32 v37, -v35, v34, v33
	v_fma_f32 v38, -v36, v34, v33
	v_cmp_ge_f32_e64 s[8:9], 0, v37
	s_nop 1
	v_cndmask_b32_e64 v34, v34, v35, s[8:9]
	v_cmp_lt_f32_e64 s[8:9], 0, v38
	s_nop 1
	v_cndmask_b32_e64 v34, v34, v36, s[8:9]
	v_mul_f32_e32 v35, 0x37800000, v34
	v_cndmask_b32_e32 v34, v34, v35, vcc
	v_cmp_class_f32_e32 vcc, v33, v172
	s_nop 1
	v_cndmask_b32_e32 v34, v34, v33, vcc
	v_div_scale_f32 v35, s[8:9], v34, v34, s54
	v_rcp_f32_e32 v36, v35
	v_div_scale_f32 v37, vcc, s54, v34, s54
	v_ashrrev_i32_e32 v33, 31, v32
	v_fma_f32 v38, -v35, v36, 1.0
	v_fmac_f32_e32 v36, v38, v36
	v_mul_f32_e32 v38, v37, v36
	v_fma_f32 v39, -v35, v38, v37
	v_fmac_f32_e32 v38, v39, v36
	v_fma_f32 v35, -v35, v38, v37
	v_div_fmas_f32 v35, v35, v36, v38
	s_and_b64 vcc, exec, s[4:5]
	v_div_fixup_f32 v34, v35, v34, s54
	s_mov_b64 s[8:9], -1
	s_cbranch_vccnz .LBB0_428
	v_lshlrev_b64 v[44:45], 7, v[32:33]
	v_lshl_add_u64 v[40:41], v[140:141], 0, v[44:45]
	global_load_dwordx4 v[36:39], v[40:41], off
	s_nop 0
	global_load_dwordx4 v[40:43], v[40:41], off offset:16
	v_lshl_add_u64 v[48:49], v[138:139], 0, v[44:45]
	global_load_dwordx4 v[44:47], v[48:49], off
	s_nop 0
	global_load_dwordx4 v[48:51], v[48:49], off offset:16
	v_pk_mul_f32 v[52:53], v[30:31], v[34:35] op_sel_hi:[1,0]
	v_pk_mul_f32 v[56:57], v[22:23], v[34:35] op_sel_hi:[1,0]
	v_pk_mul_f32 v[66:67], v[16:17], v[34:35] op_sel_hi:[1,0]
	v_mov_b64_e32 v[68:69], s[86:87]
	v_pk_mul_f32 v[54:55], v[28:29], v[34:35] op_sel_hi:[1,0]
	v_pk_mul_f32 v[58:59], v[20:21], v[34:35] op_sel_hi:[1,0]
	v_pk_mul_f32 v[62:63], v[24:25], v[34:35] op_sel_hi:[1,0]
	v_pk_mul_f32 v[64:65], v[18:19], v[34:35] op_sel_hi:[1,0]
	v_mad_i64_i32 v[68:69], s[8:9], v32, s55, v[68:69]
	v_pk_mul_f32 v[60:61], v[26:27], v[34:35] op_sel_hi:[1,0]
	v_lshl_add_u64 v[68:69], s[2:3], 1, v[68:69]
	v_lshl_add_u64 v[68:69], v[68:69], 0, v[128:129]
	s_mov_b64 s[8:9], 0
	s_waitcnt vmcnt(3)
	v_pk_mul_f32 v[70:71], v[56:57], v[38:39]
	v_pk_mul_f32 v[38:39], v[52:53], v[38:39]
	s_waitcnt vmcnt(2)
	v_pk_mul_f32 v[76:77], v[66:67], v[40:41]
	v_pk_mul_f32 v[72:73], v[58:59], v[36:37]
	v_pk_mul_f32 v[36:37], v[54:55], v[36:37]
	v_pk_mul_f32 v[74:75], v[64:65], v[42:43]
	s_waitcnt vmcnt(1)
	v_pk_fma_f32 v[52:53], v[52:53], v[46:47], v[70:71] neg_lo:[0,0,1] neg_hi:[0,0,1]
	v_pk_fma_f32 v[46:47], v[56:57], v[46:47], v[38:39]
	s_waitcnt vmcnt(0)
	v_pk_fma_f32 v[38:39], v[62:63], v[48:49], v[76:77] neg_lo:[0,0,1] neg_hi:[0,0,1]
	v_pk_mul_f32 v[42:43], v[60:61], v[42:43]
	v_pk_mul_f32 v[40:41], v[62:63], v[40:41]
	v_pk_fma_f32 v[54:55], v[54:55], v[44:45], v[72:73] neg_lo:[0,0,1] neg_hi:[0,0,1]
	v_pk_fma_f32 v[44:45], v[58:59], v[44:45], v[36:37]
	v_pk_fma_f32 v[56:57], v[60:61], v[50:51], v[74:75] neg_lo:[0,0,1] neg_hi:[0,0,1]
	v_cvt_pk_bf16_f32 v36, v54, v55
	v_cvt_pk_bf16_f32 v37, v52, v53
	v_cvt_pk_bf16_f32 v38, v38, v39
	v_pk_fma_f32 v[42:43], v[64:65], v[50:51], v[42:43]
	v_cvt_pk_bf16_f32 v39, v56, v57
	v_pk_fma_f32 v[40:41], v[66:67], v[48:49], v[40:41]
	global_store_dwordx4 v[68:69], v[36:39], off offset:256
	s_nop 1
	v_cvt_pk_bf16_f32 v36, v44, v45
	v_cvt_pk_bf16_f32 v37, v46, v47
	v_cvt_pk_bf16_f32 v38, v40, v41
	v_cvt_pk_bf16_f32 v39, v42, v43
	global_store_dwordx4 v[68:69], v[36:39], off offset:320

.LBB0_430:
	s_nop 1
	v_add_u32_e32 v16, 0xb0, v150
	v_mad_i64_i32 v[26:27], s[8:9], v16, 48, s[20:21]
	s_waitcnt vmcnt(2)
	v_mov_b32_e32 v18, v228
	v_mov_b32_e32 v19, v229
	v_mov_b32_e32 v20, v230
	v_mov_b32_e32 v21, v231
	v_mov_b32_e32 v22, v232
	v_mov_b32_e32 v23, v233
	v_mov_b32_e32 v24, v234
	v_mov_b32_e32 v25, v235
	v_mov_b32_e32 v26, v236
	v_mov_b32_e32 v27, v237
	v_mov_b32_e32 v28, v238
	v_mov_b32_e32 v29, v239
	v_add_f32_e32 v17, v18, v19
	v_add_f32_e32 v18, v20, v21
	s_nop 0
	v_add_f32_e32 v19, v22, v23
	v_add_f32_e32 v20, v24, v25
	s_nop 0
	v_add_f32_e32 v21, v26, v27
	v_add_f32_e32 v22, v28, v29
	v_add_f32_e32 v17, v17, v18
	v_add_f32_e32 v18, v19, v20
	v_add_f32_e32 v19, v21, v22
	v_add_f32_e32 v17, v17, v18
	v_add_f32_e32 v17, v17, v19
	v_fmamk_f32 v17, v17, 0x3aaaaaab, v171
	v_mul_f32_e32 v18, 0x4f800000, v17
	v_cmp_gt_f32_e32 vcc, s53, v17
	s_nop 1
	v_cndmask_b32_e32 v17, v17, v18, vcc
	v_sqrt_f32_e32 v18, v17
	s_nop 0
	v_add_u32_e32 v19, -1, v18
	v_add_u32_e32 v20, 1, v18
	v_fma_f32 v21, -v19, v18, v17
	v_fma_f32 v22, -v20, v18, v17
	v_cmp_ge_f32_e64 s[8:9], 0, v21
	s_nop 1
	v_cndmask_b32_e64 v18, v18, v19, s[8:9]
	v_cmp_lt_f32_e64 s[8:9], 0, v22
	s_nop 1
	v_cndmask_b32_e64 v18, v18, v20, s[8:9]
	v_mul_f32_e32 v19, 0x37800000, v18
	v_cndmask_b32_e32 v18, v18, v19, vcc
	v_cmp_class_f32_e32 vcc, v17, v172
	s_nop 1
	v_cndmask_b32_e32 v18, v18, v17, vcc
	v_div_scale_f32 v19, s[8:9], v18, v18, s54
	v_rcp_f32_e32 v20, v19
	v_div_scale_f32 v21, vcc, s54, v18, s54
	v_ashrrev_i32_e32 v17, 31, v16
	v_fma_f32 v22, -v19, v20, 1.0
	v_fmac_f32_e32 v20, v22, v20
	v_mul_f32_e32 v22, v21, v20
	v_fma_f32 v23, -v19, v22, v21
	v_fmac_f32_e32 v22, v23, v20
	v_fma_f32 v19, -v19, v22, v21
	v_div_fmas_f32 v19, v19, v20, v22
	s_and_b64 vcc, exec, s[4:5]
	v_div_fixup_f32 v18, v19, v18, s54
	s_mov_b64 s[4:5], -1
	s_cbranch_vccnz .LBB0_433
	v_lshlrev_b64 v[28:29], 7, v[16:17]
	v_lshl_add_u64 v[24:25], v[140:141], 0, v[28:29]
	global_load_dwordx4 v[20:23], v[24:25], off
	s_nop 0
	global_load_dwordx4 v[24:27], v[24:25], off offset:16
	v_lshl_add_u64 v[32:33], v[138:139], 0, v[28:29]
	global_load_dwordx4 v[28:31], v[32:33], off
	s_nop 0
	global_load_dwordx4 v[32:35], v[32:33], off offset:16
	v_pk_mul_f32 v[36:37], v[14:15], v[18:19] op_sel_hi:[1,0]
	v_pk_mul_f32 v[40:41], v[6:7], v[18:19] op_sel_hi:[1,0]
	v_pk_mul_f32 v[50:51], v[0:1], v[18:19] op_sel_hi:[1,0]
	v_mov_b64_e32 v[52:53], s[86:87]
	v_pk_mul_f32 v[38:39], v[12:13], v[18:19] op_sel_hi:[1,0]
	v_pk_mul_f32 v[42:43], v[4:5], v[18:19] op_sel_hi:[1,0]
	v_pk_mul_f32 v[46:47], v[8:9], v[18:19] op_sel_hi:[1,0]
	v_pk_mul_f32 v[48:49], v[2:3], v[18:19] op_sel_hi:[1,0]
	v_mad_i64_i32 v[52:53], s[4:5], v16, s55, v[52:53]
	v_pk_mul_f32 v[44:45], v[10:11], v[18:19] op_sel_hi:[1,0]
	v_lshl_add_u64 v[52:53], s[2:3], 1, v[52:53]
	v_lshl_add_u64 v[52:53], v[52:53], 0, v[128:129]
	s_waitcnt vmcnt(3)
	v_pk_mul_f32 v[54:55], v[40:41], v[22:23]
	v_pk_mul_f32 v[22:23], v[36:37], v[22:23]
	s_waitcnt vmcnt(2)
	v_pk_mul_f32 v[60:61], v[50:51], v[24:25]
	v_pk_mul_f32 v[56:57], v[42:43], v[20:21]
	v_pk_mul_f32 v[20:21], v[38:39], v[20:21]
	v_pk_mul_f32 v[58:59], v[48:49], v[26:27]
	s_waitcnt vmcnt(1)
	v_pk_fma_f32 v[36:37], v[36:37], v[30:31], v[54:55] neg_lo:[0,0,1] neg_hi:[0,0,1]
	v_pk_fma_f32 v[30:31], v[40:41], v[30:31], v[22:23]
	s_waitcnt vmcnt(0)
	v_pk_fma_f32 v[22:23], v[46:47], v[32:33], v[60:61] neg_lo:[0,0,1] neg_hi:[0,0,1]
	v_pk_mul_f32 v[26:27], v[44:45], v[26:27]
	v_pk_mul_f32 v[24:25], v[46:47], v[24:25]
	v_pk_fma_f32 v[38:39], v[38:39], v[28:29], v[56:57] neg_lo:[0,0,1] neg_hi:[0,0,1]
	v_pk_fma_f32 v[28:29], v[42:43], v[28:29], v[20:21]
	v_pk_fma_f32 v[40:41], v[44:45], v[34:35], v[58:59] neg_lo:[0,0,1] neg_hi:[0,0,1]
	v_cvt_pk_bf16_f32 v20, v38, v39
	v_cvt_pk_bf16_f32 v21, v36, v37
	v_cvt_pk_bf16_f32 v22, v22, v23
	v_pk_fma_f32 v[26:27], v[48:49], v[34:35], v[26:27]
	v_cvt_pk_bf16_f32 v23, v40, v41
	v_pk_fma_f32 v[24:25], v[50:51], v[32:33], v[24:25]
	global_store_dwordx4 v[52:53], v[20:23], off offset:256
	s_nop 1
	v_cvt_pk_bf16_f32 v20, v28, v29
	v_cvt_pk_bf16_f32 v21, v30, v31
	v_cvt_pk_bf16_f32 v22, v24, v25
	v_cvt_pk_bf16_f32 v23, v26, v27
	global_store_dwordx4 v[52:53], v[20:23], off offset:320
	s_cbranch_execz .LBB0_434

.LBB0_520:
	s_lshl_b32 s9, s1, 8
	s_lshl_b32 s0, s2, 5
	s_add_i32 s8, s0, s9
	v_or_b32_e32 v176, s8, v184
	s_movk_i32 s6, 0xc00
	v_mad_i64_i32 v[12:13], s[6:7], v176, s6, v[174:175]
	global_load_dwordx4 v[112:115], v[12:13], off
	global_load_dwordx4 v[116:119], v[12:13], off offset:32
	global_load_dwordx4 v[120:123], v[12:13], off offset:64
	global_load_dwordx4 v[124:127], v[12:13], off offset:96
	global_load_dwordx4 v[128:131], v[12:13], off offset:128
	global_load_dwordx4 v[132:135], v[12:13], off offset:160
	global_load_dwordx4 v[136:139], v[12:13], off offset:192
	global_load_dwordx4 v[140:143], v[12:13], off offset:224
	global_load_dwordx4 v[8:11], v[12:13], off offset:256
	global_load_dwordx4 v[16:19], v[12:13], off offset:288
	global_load_dwordx4 v[20:23], v[12:13], off offset:320
	global_load_dwordx4 v[24:27], v[12:13], off offset:352
	v_lshl_add_u32 v169, s2, 12, v186
	s_mov_b64 s[6:7], -1
	s_and_b64 vcc, exec, s[4:5]
	s_waitcnt vmcnt(0)
	ds_write_b128 v169, v[8:11]
	ds_write_b128 v169, v[16:19] offset:1024
	ds_write_b128 v169, v[20:23] offset:2048
	ds_write_b128 v169, v[24:27] offset:3072
	s_waitcnt vmcnt(0)
	s_cbranch_vccz .LBB0_552
	s_waitcnt vmcnt(0) lgkmcnt(0)
	s_barrier
	s_lshl_b32 s10, s2, 1
	s_and_b32 s6, s10, 4
	s_cbranch_execz .LBB0_553
